# barrier leader kernarg load and LDS set-up reads hoisted above the first s_barrier (on top of v28)
# speedup vs baseline: 1.0011x; 1.0011x over previous
.Lnorm0_done:
.LBB0_280:
	s_or_b64 exec, exec, s[16:17]
	s_mov_b64 s[8:9], s[0:1]
	s_waitcnt vmcnt(0)
	v_readlane_b32 s6, v255, 3
	s_load_dwordx2 s[4:5], s[8:9], 0x98
	s_nop 0
	v_mov_b32_e32 v0, s6
	ds_read_b32 v2, v0
	v_readlane_b32 s6, v255, 4
	s_nop 1
	v_mov_b32_e32 v0, s6
	ds_read_b32 v0, v0
	s_barrier
	s_waitcnt lgkmcnt(0)
	s_nop 0
	v_readfirstlane_b32 vcc_lo, v147
	s_nop 1
	s_cmp_eq_u32 vcc_lo, 64
	s_cbranch_scc0 .Lxb_noinv_1
	buffer_inv sc1
	s_waitcnt vmcnt(0)
.Lxb_noinv_1:
	v_cmp_eq_u32_e32 vcc, 0, v147
	s_and_saveexec_b64 s[0:1], vcc
	s_cbranch_execz .LBB0_332
	s_waitcnt vmcnt(0) expcnt(0) lgkmcnt(0)
	s_getreg_b32 s2, hwreg(HW_REG_XCC_ID, 0, 4)
	s_and_b32 s2, s2, 15
	s_waitcnt lgkmcnt(0)
	v_cmp_ne_u32_e32 vcc, 0, v2
	s_cbranch_vccnz .LBB0_296
	s_add_u32 s6, s4, 0x4200
	s_addc_u32 s7, s5, 0
	s_add_u32 s10, s4, 0x4400
	s_addc_u32 s11, s5, 0
	s_add_u32 s12, s4, 0x4500
	s_addc_u32 s13, s5, 0
	s_add_u32 s14, s4, 0x4600
	s_addc_u32 s15, s5, 0
	s_add_u32 s16, s4, 0x4700
	s_addc_u32 s17, s5, 0
	s_add_u32 s18, s4, 0x4800
	s_addc_u32 s19, s5, 0
	s_add_u32 s20, s4, 0x4900
	s_addc_u32 s21, s5, 0
	s_add_u32 s22, s4, 0x4a00
	s_addc_u32 s23, s5, 0
	s_add_u32 s24, s4, 0x4b00
	s_addc_u32 s25, s5, 0
	s_add_u32 s42, s4, 0x4c00
	s_addc_u32 s43, s5, 0
	s_add_u32 s54, s4, 0x4d00
	s_addc_u32 s55, s5, 0
	s_add_u32 s56, s4, 0x4e00
	s_addc_u32 s57, s5, 0
	s_add_u32 s58, s4, 0x4f00
	s_addc_u32 s59, s5, 0
	s_add_u32 s60, s4, 0x5000
	s_addc_u32 s61, s5, 0
	s_add_u32 s62, s4, 0x5100
	s_addc_u32 s63, s5, 0
	s_add_u32 s64, s4, 0x5200
	s_addc_u32 s65, s5, 0
	s_add_u32 s74, s4, 0x5300
	s_addc_u32 s75, s5, 0
	s_mov_b32 s26, 1
	s_branch .LBB0_284

.LBB0_385:
	s_waitcnt vmcnt(0)
	s_waitcnt vmcnt(0)
	v_readlane_b32 s7, v255, 3
	s_load_dwordx2 s[4:5], s[8:9], 0x98
	s_nop 0
	v_mov_b32_e32 v0, s7
	ds_read_b32 v2, v0
	v_readlane_b32 s7, v255, 4
	s_nop 1
	v_mov_b32_e32 v0, s7
	ds_read_b32 v0, v0
	s_barrier
	s_waitcnt lgkmcnt(0)
	s_nop 0
	v_readfirstlane_b32 vcc_lo, v147
	s_nop 1
	s_cmp_eq_u32 vcc_lo, 64
	s_cbranch_scc0 .Lxb_noinv_2
	buffer_inv sc1
	s_waitcnt vmcnt(0)
.Lxb_noinv_2:
	v_cmp_eq_u32_e32 vcc, 0, v147
	s_and_saveexec_b64 s[0:1], vcc
	s_xor_b64 s[0:1], exec, s[0:1]
	s_cbranch_execz .LBB0_438
	s_waitcnt vmcnt(0) expcnt(0) lgkmcnt(0)
	s_getreg_b32 s6, hwreg(HW_REG_XCC_ID, 0, 4)
	s_and_b32 s26, s6, 15
	s_waitcnt lgkmcnt(0)
	v_cmp_ne_u32_e32 vcc, 0, v2
	s_cbranch_vccnz .LBB0_401
	s_add_u32 s6, s4, 0x4200
	s_addc_u32 s7, s5, 0
	s_add_u32 s10, s4, 0x4400
	s_addc_u32 s11, s5, 0
	s_add_u32 s12, s4, 0x4500
	s_addc_u32 s13, s5, 0
	s_add_u32 s14, s4, 0x4600
	s_addc_u32 s15, s5, 0
	s_add_u32 s16, s4, 0x4700
	s_addc_u32 s17, s5, 0
	s_add_u32 s18, s4, 0x4800
	s_addc_u32 s19, s5, 0
	s_add_u32 s20, s4, 0x4900
	s_addc_u32 s21, s5, 0
	s_add_u32 s22, s4, 0x4a00
	s_addc_u32 s23, s5, 0
	s_add_u32 s24, s4, 0x4b00
	s_addc_u32 s25, s5, 0
	s_add_u32 s42, s4, 0x4c00
	s_addc_u32 s43, s5, 0
	s_add_u32 s54, s4, 0x4d00
	s_addc_u32 s55, s5, 0
	s_add_u32 s56, s4, 0x4e00
	s_addc_u32 s57, s5, 0
	s_add_u32 s58, s4, 0x4f00
	s_addc_u32 s59, s5, 0
	s_add_u32 s60, s4, 0x5000
	s_addc_u32 s61, s5, 0
	s_add_u32 s62, s4, 0x5100
	s_addc_u32 s63, s5, 0
	s_add_u32 s64, s4, 0x5200
	s_addc_u32 s65, s5, 0
	s_add_u32 s88, s4, 0x5300
	s_addc_u32 s89, s5, 0
	s_mov_b32 s27, 1
	s_branch .LBB0_389

.LBB0_466:
	s_waitcnt vmcnt(0)
	s_waitcnt vmcnt(0)
	v_readlane_b32 s8, v255, 3
	s_load_dwordx2 s[6:7], s[0:1], 0x98
	s_nop 0
	v_mov_b32_e32 v0, s8
	ds_read_b32 v2, v0
	v_readlane_b32 s8, v255, 4
	s_nop 1
	v_mov_b32_e32 v0, s8
	ds_read_b32 v0, v0
	s_barrier
	s_waitcnt lgkmcnt(0)
	s_nop 0
	v_readfirstlane_b32 vcc_lo, v147
	s_nop 1
	s_cmp_eq_u32 vcc_lo, 64
	s_cbranch_scc0 .Lxb_noinv_3
	buffer_inv sc1
	s_waitcnt vmcnt(0)
.Lxb_noinv_3:
	v_cmp_eq_u32_e32 vcc, 0, v147
	s_and_saveexec_b64 s[4:5], vcc
	s_xor_b64 s[4:5], exec, s[4:5]
	s_cbranch_execz .LBB0_519
	s_waitcnt vmcnt(0) expcnt(0) lgkmcnt(0)
	s_getreg_b32 s2, hwreg(HW_REG_XCC_ID, 0, 4)
	s_and_b32 s2, s2, 15
	s_waitcnt lgkmcnt(0)
	v_cmp_ne_u32_e32 vcc, 0, v2
	s_cbranch_vccnz .LBB0_482
	s_add_u32 s8, s6, 0x4200
	s_addc_u32 s9, s7, 0
	s_add_u32 s12, s6, 0x4400
	s_addc_u32 s13, s7, 0
	s_add_u32 s14, s6, 0x4500
	s_addc_u32 s15, s7, 0
	s_add_u32 s16, s6, 0x4600
	s_addc_u32 s17, s7, 0
	s_add_u32 s18, s6, 0x4700
	s_addc_u32 s19, s7, 0
	s_add_u32 s20, s6, 0x4800
	s_addc_u32 s21, s7, 0
	s_add_u32 s22, s6, 0x4900
	s_addc_u32 s23, s7, 0
	s_add_u32 s24, s6, 0x4a00
	s_addc_u32 s25, s7, 0
	s_add_u32 s42, s6, 0x4b00
	s_addc_u32 s43, s7, 0
	s_add_u32 s54, s6, 0x4c00
	s_addc_u32 s55, s7, 0
	s_add_u32 s56, s6, 0x4d00
	s_addc_u32 s57, s7, 0
	s_add_u32 s58, s6, 0x4e00
	s_addc_u32 s59, s7, 0
	s_add_u32 s60, s6, 0x4f00
	s_addc_u32 s61, s7, 0
	s_add_u32 s62, s6, 0x5000
	s_addc_u32 s63, s7, 0
	s_add_u32 s64, s6, 0x5100
	s_addc_u32 s65, s7, 0
	s_add_u32 s86, s6, 0x5200
	s_addc_u32 s87, s7, 0
	s_add_u32 s88, s6, 0x5300
	s_addc_u32 s89, s7, 0
	s_mov_b32 s26, 1
	s_branch .LBB0_470

.LBB0_523:
	s_or_b64 exec, exec, s[8:9]
	s_waitcnt vmcnt(0)
	v_readlane_b32 s8, v255, 3
	s_load_dwordx2 s[6:7], s[16:17], 0x98
	s_nop 0
	v_mov_b32_e32 v0, s8
	ds_read_b32 v2, v0
	v_readlane_b32 s8, v255, 4
	s_nop 1
	v_mov_b32_e32 v0, s8
	ds_read_b32 v0, v0
	s_barrier
	s_waitcnt lgkmcnt(0)
	s_nop 0
	v_readfirstlane_b32 vcc_lo, v147
	s_nop 1
	s_cmp_eq_u32 vcc_lo, 64
	s_cbranch_scc0 .Lxb_noinv_4
	buffer_inv sc1
	s_waitcnt vmcnt(0)
.Lxb_noinv_4:
	v_cmp_eq_u32_e32 vcc, 0, v147
	s_and_saveexec_b64 s[4:5], vcc
	s_cbranch_execz .LBB0_575
	s_waitcnt vmcnt(0) expcnt(0) lgkmcnt(0)
	s_getreg_b32 s2, hwreg(HW_REG_XCC_ID, 0, 4)
	s_and_b32 s2, s2, 15
	s_waitcnt lgkmcnt(0)
	v_cmp_ne_u32_e32 vcc, 0, v2
	s_cbranch_vccnz .LBB0_539
	s_add_u32 s8, s6, 0x4200
	s_addc_u32 s9, s7, 0
	s_add_u32 s10, s6, 0x4400
	s_addc_u32 s11, s7, 0
	s_add_u32 s12, s6, 0x4500
	s_addc_u32 s13, s7, 0
	s_add_u32 s14, s6, 0x4600
	s_addc_u32 s15, s7, 0
	s_add_u32 s18, s6, 0x4700
	s_addc_u32 s19, s7, 0
	s_add_u32 s20, s6, 0x4800
	s_addc_u32 s21, s7, 0
	s_add_u32 s22, s6, 0x4900
	s_addc_u32 s23, s7, 0
	s_add_u32 s24, s6, 0x4a00
	s_addc_u32 s25, s7, 0
	s_add_u32 s42, s6, 0x4b00
	s_addc_u32 s43, s7, 0
	s_add_u32 s54, s6, 0x4c00
	s_addc_u32 s55, s7, 0
	s_add_u32 s56, s6, 0x4d00
	s_addc_u32 s57, s7, 0
	s_add_u32 s58, s6, 0x4e00
	s_addc_u32 s59, s7, 0
	s_add_u32 s60, s6, 0x4f00
	s_addc_u32 s61, s7, 0
	s_add_u32 s62, s6, 0x5000
	s_addc_u32 s63, s7, 0
	s_add_u32 s64, s6, 0x5100
	s_addc_u32 s65, s7, 0
	s_add_u32 s88, s6, 0x5200
	s_addc_u32 s89, s7, 0
	s_add_u32 s90, s6, 0x5300
	s_addc_u32 s91, s7, 0
	s_mov_b32 s26, 1
	s_branch .LBB0_527

.LBB0_921:
	s_waitcnt vmcnt(0)
	s_waitcnt vmcnt(0) lgkmcnt(0)
	v_readlane_b32 s8, v255, 3
	s_load_dwordx2 s[6:7], s[16:17], 0x98
	s_nop 0
	v_mov_b32_e32 v0, s8
	ds_read_b32 v2, v0
	v_readlane_b32 s8, v255, 4
	s_nop 1
	v_mov_b32_e32 v0, s8
	ds_read_b32 v0, v0
	s_barrier
	s_waitcnt lgkmcnt(0)
	s_nop 0
	v_readfirstlane_b32 vcc_lo, v147
	s_nop 1
	s_cmp_eq_u32 vcc_lo, 64
	s_cbranch_scc0 .Lxb_noinv_5
	buffer_inv sc1
	s_waitcnt vmcnt(0)

.LBB0_1093:
	s_waitcnt vmcnt(0)
	v_readlane_b32 s10, v255, 3
	s_load_dwordx2 s[6:7], s[8:9], 0x98
	s_nop 0
	v_mov_b32_e32 v0, s10
	ds_read_b32 v2, v0
	v_readlane_b32 s10, v255, 4
	s_nop 1
	v_mov_b32_e32 v0, s10
	ds_read_b32 v0, v0
	s_barrier
	s_waitcnt lgkmcnt(0)
	s_nop 0
	v_readfirstlane_b32 vcc_lo, v147
	s_nop 1
	s_cmp_eq_u32 vcc_lo, 64
	s_cbranch_scc0 .Lxb_noinv_6
	buffer_inv sc1
	s_waitcnt vmcnt(0)
.Lxb_noinv_6:
	v_cmp_eq_u32_e32 vcc, 0, v147
	s_and_saveexec_b64 s[4:5], vcc
	s_cbranch_execz .LBB0_1145
	s_waitcnt vmcnt(0) expcnt(0) lgkmcnt(0)
	s_getreg_b32 s2, hwreg(HW_REG_XCC_ID, 0, 4)
	s_and_b32 s2, s2, 15
	s_waitcnt lgkmcnt(0)
	v_cmp_ne_u32_e32 vcc, 0, v2
	s_cbranch_vccnz .LBB0_1109
	s_add_u32 s10, s6, 0x4200
	s_addc_u32 s11, s7, 0
	s_add_u32 s12, s6, 0x4400
	s_addc_u32 s13, s7, 0
	s_add_u32 s14, s6, 0x4500
	s_addc_u32 s15, s7, 0
	s_add_u32 s16, s6, 0x4600
	s_addc_u32 s17, s7, 0
	s_add_u32 s18, s6, 0x4700
	s_addc_u32 s19, s7, 0
	s_add_u32 s20, s6, 0x4800
	s_addc_u32 s21, s7, 0
	s_add_u32 s22, s6, 0x4900
	s_addc_u32 s23, s7, 0
	s_add_u32 s24, s6, 0x4a00
	s_addc_u32 s25, s7, 0
	s_add_u32 s42, s6, 0x4b00
	s_addc_u32 s43, s7, 0
	s_add_u32 s54, s6, 0x4c00
	s_addc_u32 s55, s7, 0
	s_add_u32 s56, s6, 0x4d00
	s_addc_u32 s57, s7, 0
	s_add_u32 s58, s6, 0x4e00
	s_addc_u32 s59, s7, 0
	s_add_u32 s60, s6, 0x4f00
	s_addc_u32 s61, s7, 0
	s_add_u32 s62, s6, 0x5000
	s_addc_u32 s63, s7, 0
	s_add_u32 s64, s6, 0x5100
	s_addc_u32 s65, s7, 0
	s_add_u32 s88, s6, 0x5200
	s_addc_u32 s89, s7, 0
	s_add_u32 s90, s6, 0x5300
	s_addc_u32 s91, s7, 0
	s_mov_b32 s26, 1
	s_branch .LBB0_1097

.LBB0_1169:
	s_waitcnt vmcnt(0)
	s_waitcnt vmcnt(0)
	v_readlane_b32 s10, v255, 3
	s_load_dwordx2 s[6:7], s[8:9], 0x98
	s_nop 0
	v_mov_b32_e32 v0, s10
	ds_read_b32 v2, v0
	v_readlane_b32 s10, v255, 4
	s_nop 1
	v_mov_b32_e32 v0, s10
	ds_read_b32 v0, v0
	s_barrier
	s_waitcnt lgkmcnt(0)
	s_nop 0
	v_readfirstlane_b32 vcc_lo, v147
	s_nop 1
	s_cmp_eq_u32 vcc_lo, 64
	s_cbranch_scc0 .Lxb_noinv_7
	buffer_inv sc1
	s_waitcnt vmcnt(0)
.Lxb_noinv_7:
	v_cmp_eq_u32_e32 vcc, 0, v147
	s_and_saveexec_b64 s[4:5], vcc
	s_xor_b64 s[4:5], exec, s[4:5]
	s_cbranch_execz .LBB0_1222
	s_waitcnt vmcnt(0) expcnt(0) lgkmcnt(0)
	s_getreg_b32 s2, hwreg(HW_REG_XCC_ID, 0, 4)
	s_and_b32 s2, s2, 15
	s_waitcnt lgkmcnt(0)
	v_cmp_ne_u32_e32 vcc, 0, v2
	s_cbranch_vccnz .LBB0_1185
	s_add_u32 s10, s6, 0x4200
	s_addc_u32 s11, s7, 0
	s_add_u32 s12, s6, 0x4400
	s_addc_u32 s13, s7, 0
	s_add_u32 s14, s6, 0x4500
	s_addc_u32 s15, s7, 0
	s_add_u32 s16, s6, 0x4600
	s_addc_u32 s17, s7, 0
	s_add_u32 s18, s6, 0x4700
	s_addc_u32 s19, s7, 0
	s_add_u32 s20, s6, 0x4800
	s_addc_u32 s21, s7, 0
	s_add_u32 s22, s6, 0x4900
	s_addc_u32 s23, s7, 0
	s_add_u32 s24, s6, 0x4a00
	s_addc_u32 s25, s7, 0
	s_add_u32 s42, s6, 0x4b00
	s_addc_u32 s43, s7, 0
	s_add_u32 s54, s6, 0x4c00
	s_addc_u32 s55, s7, 0
	s_add_u32 s56, s6, 0x4d00
	s_addc_u32 s57, s7, 0
	s_add_u32 s58, s6, 0x4e00
	s_addc_u32 s59, s7, 0
	s_add_u32 s60, s6, 0x4f00
	s_addc_u32 s61, s7, 0
	s_add_u32 s62, s6, 0x5000
	s_addc_u32 s63, s7, 0
	s_add_u32 s64, s6, 0x5100
	s_addc_u32 s65, s7, 0
	s_add_u32 s88, s6, 0x5200
	s_addc_u32 s89, s7, 0
	s_add_u32 s90, s6, 0x5300
	s_addc_u32 s91, s7, 0
	s_mov_b32 s26, 1
	s_branch .LBB0_1173

.LBB0_1225:
	s_or_b64 exec, exec, s[10:11]
	s_waitcnt vmcnt(0)
	v_readlane_b32 s10, v255, 3
	s_load_dwordx2 s[6:7], s[8:9], 0x98
	s_nop 0
	v_mov_b32_e32 v0, s10
	ds_read_b32 v2, v0
	v_readlane_b32 s10, v255, 4
	s_nop 1
	v_mov_b32_e32 v0, s10
	ds_read_b32 v0, v0
	s_barrier
	s_waitcnt lgkmcnt(0)
	s_nop 0
	v_readfirstlane_b32 vcc_lo, v147
	s_nop 1
	s_cmp_eq_u32 vcc_lo, 64
	s_cbranch_scc0 .Lxb_noinv_8
	buffer_inv sc1
	s_waitcnt vmcnt(0)
